# job_mod silu staging loop: all 36 loads issued up front with counted vmcnt instead of load-wait-compute per element (on top of PEER stage B + GEMM loops)
# speedup vs baseline: 1.0412x; 1.0113x over previous
.LBB0_86:
	s_andn2_b64 vcc, exec, s[0:1]
	s_cbranch_vccnz .LBB0_8
	v_mov_b32_e32 v2, v156
	s_movk_i32 s0, 0x47ff
	s_nop 0
	v_cmp_lt_i32_e32 vcc, s0, v2
	v_lshlrev_b32_e32 v11, 2, v2
	s_barrier
	s_and_saveexec_b64 s[0:1], vcc
	s_xor_b64 s[0:1], exec, s[0:1]
	v_lshlrev_b32_e32 v11, 2, v2
	s_andn2_saveexec_b64 s[0:1], s[0:1]
	s_cbranch_execz .LBB0_93
	global_load_dword v166, v11, s[54:55]
	global_load_dword v167, v11, s[54:55] offset:2048
	v_add_u32_e32 v203, 0x1000, v11
	global_load_dword v168, v203, s[54:55]
	global_load_dword v169, v203, s[54:55] offset:2048
	v_add_u32_e32 v202, 0x2000, v11
	global_load_dword v170, v202, s[54:55]
	global_load_dword v171, v202, s[54:55] offset:2048
	v_add_u32_e32 v203, 0x3000, v11
	global_load_dword v172, v203, s[54:55]
	global_load_dword v173, v203, s[54:55] offset:2048
	v_add_u32_e32 v202, 0x4000, v11
	global_load_dword v174, v202, s[54:55]
	global_load_dword v175, v202, s[54:55] offset:2048
	v_add_u32_e32 v203, 0x5000, v11
	global_load_dword v176, v203, s[54:55]
	global_load_dword v177, v203, s[54:55] offset:2048
	v_add_u32_e32 v202, 0x6000, v11
	global_load_dword v178, v202, s[54:55]
	global_load_dword v179, v202, s[54:55] offset:2048
	v_add_u32_e32 v203, 0x7000, v11
	global_load_dword v180, v203, s[54:55]
	global_load_dword v181, v203, s[54:55] offset:2048
	v_add_u32_e32 v202, 0x8000, v11
	global_load_dword v182, v202, s[54:55]
	global_load_dword v183, v202, s[54:55] offset:2048
	v_add_u32_e32 v203, 0x9000, v11
	global_load_dword v184, v203, s[54:55]
	global_load_dword v185, v203, s[54:55] offset:2048
	v_add_u32_e32 v202, 0xa000, v11
	global_load_dword v186, v202, s[54:55]
	global_load_dword v187, v202, s[54:55] offset:2048
	v_add_u32_e32 v203, 0xb000, v11
	global_load_dword v188, v203, s[54:55]
	global_load_dword v189, v203, s[54:55] offset:2048
	v_add_u32_e32 v202, 0xc000, v11
	global_load_dword v190, v202, s[54:55]
	global_load_dword v191, v202, s[54:55] offset:2048
	v_add_u32_e32 v203, 0xd000, v11
	global_load_dword v192, v203, s[54:55]
	global_load_dword v193, v203, s[54:55] offset:2048
	v_add_u32_e32 v202, 0xe000, v11
	global_load_dword v194, v202, s[54:55]
	global_load_dword v195, v202, s[54:55] offset:2048
	v_add_u32_e32 v203, 0xf000, v11
	global_load_dword v196, v203, s[54:55]
	global_load_dword v197, v203, s[54:55] offset:2048
	global_load_dword v198, v11, s[58:59]
	global_load_dword v199, v11, s[58:59] offset:2048
	v_add_u32_e32 v202, 0x1000, v11
	global_load_dword v200, v202, s[58:59]
	global_load_dword v201, v202, s[58:59] offset:2048
	v_add_u32_e32 v203, 0x10000, v11
	s_waitcnt vmcnt(35)
	v_mul_f32_e32 v204, 0xbfb8aa3b, v166
	v_exp_f32_e32 v204, v204
	s_nop 0
	v_add_f32_e32 v204, 1.0, v204
	v_div_scale_f32 v205, s[10:11], v204, v204, v166
	v_rcp_f32_e32 v206, v205
	v_div_scale_f32 v207, vcc, v166, v204, v166
	v_fma_f32 v208, -v205, v206, 1.0
	v_fmac_f32_e32 v206, v208, v206
	v_mul_f32_e32 v208, v207, v206
	v_fma_f32 v209, -v205, v208, v207
	v_fmac_f32_e32 v208, v209, v206
	v_fma_f32 v205, -v205, v208, v207
	v_div_fmas_f32 v205, v205, v206, v208
	v_div_fixup_f32 v166, v205, v204, v166
	ds_write_b32 v11, v166
	s_waitcnt vmcnt(34)
	v_mul_f32_e32 v204, 0xbfb8aa3b, v167
	v_exp_f32_e32 v204, v204
	s_nop 0
	v_add_f32_e32 v204, 1.0, v204
	v_div_scale_f32 v205, s[10:11], v204, v204, v167
	v_rcp_f32_e32 v206, v205
	v_div_scale_f32 v207, vcc, v167, v204, v167
	v_fma_f32 v208, -v205, v206, 1.0
	v_fmac_f32_e32 v206, v208, v206
	v_mul_f32_e32 v208, v207, v206
	v_fma_f32 v209, -v205, v208, v207
	v_fmac_f32_e32 v208, v209, v206
	v_fma_f32 v205, -v205, v208, v207
	v_div_fmas_f32 v205, v205, v206, v208
	v_div_fixup_f32 v167, v205, v204, v167
	ds_write_b32 v11, v167 offset:2048
	s_waitcnt vmcnt(33)
	v_mul_f32_e32 v204, 0xbfb8aa3b, v168
	v_exp_f32_e32 v204, v204
	s_nop 0
	v_add_f32_e32 v204, 1.0, v204
	v_div_scale_f32 v205, s[10:11], v204, v204, v168
	v_rcp_f32_e32 v206, v205
	v_div_scale_f32 v207, vcc, v168, v204, v168
	v_fma_f32 v208, -v205, v206, 1.0
	v_fmac_f32_e32 v206, v208, v206
	v_mul_f32_e32 v208, v207, v206
	v_fma_f32 v209, -v205, v208, v207
	v_fmac_f32_e32 v208, v209, v206
	v_fma_f32 v205, -v205, v208, v207
	v_div_fmas_f32 v205, v205, v206, v208
	v_div_fixup_f32 v168, v205, v204, v168
	ds_write_b32 v11, v168 offset:4096
	s_waitcnt vmcnt(32)
	v_mul_f32_e32 v204, 0xbfb8aa3b, v169
	v_exp_f32_e32 v204, v204
	s_nop 0
	v_add_f32_e32 v204, 1.0, v204
	v_div_scale_f32 v205, s[10:11], v204, v204, v169
	v_rcp_f32_e32 v206, v205
	v_div_scale_f32 v207, vcc, v169, v204, v169
	v_fma_f32 v208, -v205, v206, 1.0
	v_fmac_f32_e32 v206, v208, v206
	v_mul_f32_e32 v208, v207, v206
	v_fma_f32 v209, -v205, v208, v207
	v_fmac_f32_e32 v208, v209, v206
	v_fma_f32 v205, -v205, v208, v207
	v_div_fmas_f32 v205, v205, v206, v208
	v_div_fixup_f32 v169, v205, v204, v169
	ds_write_b32 v11, v169 offset:6144
	s_waitcnt vmcnt(31)
	v_mul_f32_e32 v204, 0xbfb8aa3b, v170
	v_exp_f32_e32 v204, v204
	s_nop 0
	v_add_f32_e32 v204, 1.0, v204
	v_div_scale_f32 v205, s[10:11], v204, v204, v170
	v_rcp_f32_e32 v206, v205
	v_div_scale_f32 v207, vcc, v170, v204, v170
	v_fma_f32 v208, -v205, v206, 1.0
	v_fmac_f32_e32 v206, v208, v206
	v_mul_f32_e32 v208, v207, v206
	v_fma_f32 v209, -v205, v208, v207
	v_fmac_f32_e32 v208, v209, v206
	v_fma_f32 v205, -v205, v208, v207
	v_div_fmas_f32 v205, v205, v206, v208
	v_div_fixup_f32 v170, v205, v204, v170
	ds_write_b32 v11, v170 offset:8192
	s_waitcnt vmcnt(30)
	v_mul_f32_e32 v204, 0xbfb8aa3b, v171
	v_exp_f32_e32 v204, v204
	s_nop 0
	v_add_f32_e32 v204, 1.0, v204
	v_div_scale_f32 v205, s[10:11], v204, v204, v171
	v_rcp_f32_e32 v206, v205
	v_div_scale_f32 v207, vcc, v171, v204, v171
	v_fma_f32 v208, -v205, v206, 1.0
	v_fmac_f32_e32 v206, v208, v206
	v_mul_f32_e32 v208, v207, v206
	v_fma_f32 v209, -v205, v208, v207
	v_fmac_f32_e32 v208, v209, v206
	v_fma_f32 v205, -v205, v208, v207
	v_div_fmas_f32 v205, v205, v206, v208
	v_div_fixup_f32 v171, v205, v204, v171
	ds_write_b32 v11, v171 offset:10240
	s_waitcnt vmcnt(29)
	v_mul_f32_e32 v204, 0xbfb8aa3b, v172
	v_exp_f32_e32 v204, v204
	s_nop 0
	v_add_f32_e32 v204, 1.0, v204
	v_div_scale_f32 v205, s[10:11], v204, v204, v172
	v_rcp_f32_e32 v206, v205
	v_div_scale_f32 v207, vcc, v172, v204, v172
	v_fma_f32 v208, -v205, v206, 1.0
	v_fmac_f32_e32 v206, v208, v206
	v_mul_f32_e32 v208, v207, v206
	v_fma_f32 v209, -v205, v208, v207
	v_fmac_f32_e32 v208, v209, v206
	v_fma_f32 v205, -v205, v208, v207
	v_div_fmas_f32 v205, v205, v206, v208
	v_div_fixup_f32 v172, v205, v204, v172
	ds_write_b32 v11, v172 offset:12288
	s_waitcnt vmcnt(28)
	v_mul_f32_e32 v204, 0xbfb8aa3b, v173
	v_exp_f32_e32 v204, v204
	s_nop 0
	v_add_f32_e32 v204, 1.0, v204
	v_div_scale_f32 v205, s[10:11], v204, v204, v173
	v_rcp_f32_e32 v206, v205
	v_div_scale_f32 v207, vcc, v173, v204, v173
	v_fma_f32 v208, -v205, v206, 1.0
	v_fmac_f32_e32 v206, v208, v206
	v_mul_f32_e32 v208, v207, v206
	v_fma_f32 v209, -v205, v208, v207
	v_fmac_f32_e32 v208, v209, v206
	v_fma_f32 v205, -v205, v208, v207
	v_div_fmas_f32 v205, v205, v206, v208
	v_div_fixup_f32 v173, v205, v204, v173
	ds_write_b32 v11, v173 offset:14336
	s_waitcnt vmcnt(27)
	v_mul_f32_e32 v204, 0xbfb8aa3b, v174
	v_exp_f32_e32 v204, v204
	s_nop 0
	v_add_f32_e32 v204, 1.0, v204
	v_div_scale_f32 v205, s[10:11], v204, v204, v174
	v_rcp_f32_e32 v206, v205
	v_div_scale_f32 v207, vcc, v174, v204, v174
	v_fma_f32 v208, -v205, v206, 1.0
	v_fmac_f32_e32 v206, v208, v206
	v_mul_f32_e32 v208, v207, v206
	v_fma_f32 v209, -v205, v208, v207
	v_fmac_f32_e32 v208, v209, v206
	v_fma_f32 v205, -v205, v208, v207
	v_div_fmas_f32 v205, v205, v206, v208
	v_div_fixup_f32 v174, v205, v204, v174
	ds_write_b32 v11, v174 offset:16384
	s_waitcnt vmcnt(26)
	v_mul_f32_e32 v204, 0xbfb8aa3b, v175
	v_exp_f32_e32 v204, v204
	s_nop 0
	v_add_f32_e32 v204, 1.0, v204
	v_div_scale_f32 v205, s[10:11], v204, v204, v175
	v_rcp_f32_e32 v206, v205
	v_div_scale_f32 v207, vcc, v175, v204, v175
	v_fma_f32 v208, -v205, v206, 1.0
	v_fmac_f32_e32 v206, v208, v206
	v_mul_f32_e32 v208, v207, v206
	v_fma_f32 v209, -v205, v208, v207
	v_fmac_f32_e32 v208, v209, v206
	v_fma_f32 v205, -v205, v208, v207
	v_div_fmas_f32 v205, v205, v206, v208
	v_div_fixup_f32 v175, v205, v204, v175
	ds_write_b32 v11, v175 offset:18432
	s_waitcnt vmcnt(25)
	v_mul_f32_e32 v204, 0xbfb8aa3b, v176
	v_exp_f32_e32 v204, v204
	s_nop 0
	v_add_f32_e32 v204, 1.0, v204
	v_div_scale_f32 v205, s[10:11], v204, v204, v176
	v_rcp_f32_e32 v206, v205
	v_div_scale_f32 v207, vcc, v176, v204, v176
	v_fma_f32 v208, -v205, v206, 1.0
	v_fmac_f32_e32 v206, v208, v206
	v_mul_f32_e32 v208, v207, v206
	v_fma_f32 v209, -v205, v208, v207
	v_fmac_f32_e32 v208, v209, v206
	v_fma_f32 v205, -v205, v208, v207
	v_div_fmas_f32 v205, v205, v206, v208
	v_div_fixup_f32 v176, v205, v204, v176
	ds_write_b32 v11, v176 offset:20480
	s_waitcnt vmcnt(24)
	v_mul_f32_e32 v204, 0xbfb8aa3b, v177
	v_exp_f32_e32 v204, v204
	s_nop 0
	v_add_f32_e32 v204, 1.0, v204
	v_div_scale_f32 v205, s[10:11], v204, v204, v177
	v_rcp_f32_e32 v206, v205
	v_div_scale_f32 v207, vcc, v177, v204, v177
	v_fma_f32 v208, -v205, v206, 1.0
	v_fmac_f32_e32 v206, v208, v206
	v_mul_f32_e32 v208, v207, v206
	v_fma_f32 v209, -v205, v208, v207
	v_fmac_f32_e32 v208, v209, v206
	v_fma_f32 v205, -v205, v208, v207
	v_div_fmas_f32 v205, v205, v206, v208
	v_div_fixup_f32 v177, v205, v204, v177
	ds_write_b32 v11, v177 offset:22528
	s_waitcnt vmcnt(23)
	v_mul_f32_e32 v204, 0xbfb8aa3b, v178
	v_exp_f32_e32 v204, v204
	s_nop 0
	v_add_f32_e32 v204, 1.0, v204
	v_div_scale_f32 v205, s[10:11], v204, v204, v178
	v_rcp_f32_e32 v206, v205
	v_div_scale_f32 v207, vcc, v178, v204, v178
	v_fma_f32 v208, -v205, v206, 1.0
	v_fmac_f32_e32 v206, v208, v206
	v_mul_f32_e32 v208, v207, v206
	v_fma_f32 v209, -v205, v208, v207
	v_fmac_f32_e32 v208, v209, v206
	v_fma_f32 v205, -v205, v208, v207
	v_div_fmas_f32 v205, v205, v206, v208
	v_div_fixup_f32 v178, v205, v204, v178
	ds_write_b32 v11, v178 offset:24576
	s_waitcnt vmcnt(22)
	v_mul_f32_e32 v204, 0xbfb8aa3b, v179
	v_exp_f32_e32 v204, v204
	s_nop 0
	v_add_f32_e32 v204, 1.0, v204
	v_div_scale_f32 v205, s[10:11], v204, v204, v179
	v_rcp_f32_e32 v206, v205
	v_div_scale_f32 v207, vcc, v179, v204, v179
	v_fma_f32 v208, -v205, v206, 1.0
	v_fmac_f32_e32 v206, v208, v206
	v_mul_f32_e32 v208, v207, v206
	v_fma_f32 v209, -v205, v208, v207
	v_fmac_f32_e32 v208, v209, v206
	v_fma_f32 v205, -v205, v208, v207
	v_div_fmas_f32 v205, v205, v206, v208
	v_div_fixup_f32 v179, v205, v204, v179
	ds_write_b32 v11, v179 offset:26624
	s_waitcnt vmcnt(21)
	v_mul_f32_e32 v204, 0xbfb8aa3b, v180
	v_exp_f32_e32 v204, v204
	s_nop 0
	v_add_f32_e32 v204, 1.0, v204
	v_div_scale_f32 v205, s[10:11], v204, v204, v180
	v_rcp_f32_e32 v206, v205
	v_div_scale_f32 v207, vcc, v180, v204, v180
	v_fma_f32 v208, -v205, v206, 1.0
	v_fmac_f32_e32 v206, v208, v206
	v_mul_f32_e32 v208, v207, v206
	v_fma_f32 v209, -v205, v208, v207
	v_fmac_f32_e32 v208, v209, v206
	v_fma_f32 v205, -v205, v208, v207
	v_div_fmas_f32 v205, v205, v206, v208
	v_div_fixup_f32 v180, v205, v204, v180
	ds_write_b32 v11, v180 offset:28672
	s_waitcnt vmcnt(20)
	v_mul_f32_e32 v204, 0xbfb8aa3b, v181
	v_exp_f32_e32 v204, v204
	s_nop 0
	v_add_f32_e32 v204, 1.0, v204
	v_div_scale_f32 v205, s[10:11], v204, v204, v181
	v_rcp_f32_e32 v206, v205
	v_div_scale_f32 v207, vcc, v181, v204, v181
	v_fma_f32 v208, -v205, v206, 1.0
	v_fmac_f32_e32 v206, v208, v206
	v_mul_f32_e32 v208, v207, v206
	v_fma_f32 v209, -v205, v208, v207
	v_fmac_f32_e32 v208, v209, v206
	v_fma_f32 v205, -v205, v208, v207
	v_div_fmas_f32 v205, v205, v206, v208
	v_div_fixup_f32 v181, v205, v204, v181
	ds_write_b32 v11, v181 offset:30720
	s_waitcnt vmcnt(19)
	v_mul_f32_e32 v204, 0xbfb8aa3b, v182
	v_exp_f32_e32 v204, v204
	s_nop 0
	v_add_f32_e32 v204, 1.0, v204
	v_div_scale_f32 v205, s[10:11], v204, v204, v182
	v_rcp_f32_e32 v206, v205
	v_div_scale_f32 v207, vcc, v182, v204, v182
	v_fma_f32 v208, -v205, v206, 1.0
	v_fmac_f32_e32 v206, v208, v206
	v_mul_f32_e32 v208, v207, v206
	v_fma_f32 v209, -v205, v208, v207
	v_fmac_f32_e32 v208, v209, v206
	v_fma_f32 v205, -v205, v208, v207
	v_div_fmas_f32 v205, v205, v206, v208
	v_div_fixup_f32 v182, v205, v204, v182
	ds_write_b32 v11, v182 offset:32768
	s_waitcnt vmcnt(18)
	v_mul_f32_e32 v204, 0xbfb8aa3b, v183
	v_exp_f32_e32 v204, v204
	s_nop 0
	v_add_f32_e32 v204, 1.0, v204
	v_div_scale_f32 v205, s[10:11], v204, v204, v183
	v_rcp_f32_e32 v206, v205
	v_div_scale_f32 v207, vcc, v183, v204, v183
	v_fma_f32 v208, -v205, v206, 1.0
	v_fmac_f32_e32 v206, v208, v206
	v_mul_f32_e32 v208, v207, v206
	v_fma_f32 v209, -v205, v208, v207
	v_fmac_f32_e32 v208, v209, v206
	v_fma_f32 v205, -v205, v208, v207
	v_div_fmas_f32 v205, v205, v206, v208
	v_div_fixup_f32 v183, v205, v204, v183
	ds_write_b32 v11, v183 offset:34816
	s_waitcnt vmcnt(17)
	v_mul_f32_e32 v204, 0xbfb8aa3b, v184
	v_exp_f32_e32 v204, v204
	s_nop 0
	v_add_f32_e32 v204, 1.0, v204
	v_div_scale_f32 v205, s[10:11], v204, v204, v184
	v_rcp_f32_e32 v206, v205
	v_div_scale_f32 v207, vcc, v184, v204, v184
	v_fma_f32 v208, -v205, v206, 1.0
	v_fmac_f32_e32 v206, v208, v206
	v_mul_f32_e32 v208, v207, v206
	v_fma_f32 v209, -v205, v208, v207
	v_fmac_f32_e32 v208, v209, v206
	v_fma_f32 v205, -v205, v208, v207
	v_div_fmas_f32 v205, v205, v206, v208
	v_div_fixup_f32 v184, v205, v204, v184
	ds_write_b32 v11, v184 offset:36864
	s_waitcnt vmcnt(16)
	v_mul_f32_e32 v204, 0xbfb8aa3b, v185
	v_exp_f32_e32 v204, v204
	s_nop 0
	v_add_f32_e32 v204, 1.0, v204
	v_div_scale_f32 v205, s[10:11], v204, v204, v185
	v_rcp_f32_e32 v206, v205
	v_div_scale_f32 v207, vcc, v185, v204, v185
	v_fma_f32 v208, -v205, v206, 1.0
	v_fmac_f32_e32 v206, v208, v206
	v_mul_f32_e32 v208, v207, v206
	v_fma_f32 v209, -v205, v208, v207
	v_fmac_f32_e32 v208, v209, v206
	v_fma_f32 v205, -v205, v208, v207
	v_div_fmas_f32 v205, v205, v206, v208
	v_div_fixup_f32 v185, v205, v204, v185
	ds_write_b32 v11, v185 offset:38912
	s_waitcnt vmcnt(15)
	v_mul_f32_e32 v204, 0xbfb8aa3b, v186
	v_exp_f32_e32 v204, v204
	s_nop 0
	v_add_f32_e32 v204, 1.0, v204
	v_div_scale_f32 v205, s[10:11], v204, v204, v186
	v_rcp_f32_e32 v206, v205
	v_div_scale_f32 v207, vcc, v186, v204, v186
	v_fma_f32 v208, -v205, v206, 1.0
	v_fmac_f32_e32 v206, v208, v206
	v_mul_f32_e32 v208, v207, v206
	v_fma_f32 v209, -v205, v208, v207
	v_fmac_f32_e32 v208, v209, v206
	v_fma_f32 v205, -v205, v208, v207
	v_div_fmas_f32 v205, v205, v206, v208
	v_div_fixup_f32 v186, v205, v204, v186
	ds_write_b32 v11, v186 offset:40960
	s_waitcnt vmcnt(14)
	v_mul_f32_e32 v204, 0xbfb8aa3b, v187
	v_exp_f32_e32 v204, v204
	s_nop 0
	v_add_f32_e32 v204, 1.0, v204
	v_div_scale_f32 v205, s[10:11], v204, v204, v187
	v_rcp_f32_e32 v206, v205
	v_div_scale_f32 v207, vcc, v187, v204, v187
	v_fma_f32 v208, -v205, v206, 1.0
	v_fmac_f32_e32 v206, v208, v206
	v_mul_f32_e32 v208, v207, v206
	v_fma_f32 v209, -v205, v208, v207
	v_fmac_f32_e32 v208, v209, v206
	v_fma_f32 v205, -v205, v208, v207
	v_div_fmas_f32 v205, v205, v206, v208
	v_div_fixup_f32 v187, v205, v204, v187
	ds_write_b32 v11, v187 offset:43008
	s_waitcnt vmcnt(13)
	v_mul_f32_e32 v204, 0xbfb8aa3b, v188
	v_exp_f32_e32 v204, v204
	s_nop 0
	v_add_f32_e32 v204, 1.0, v204
	v_div_scale_f32 v205, s[10:11], v204, v204, v188
	v_rcp_f32_e32 v206, v205
	v_div_scale_f32 v207, vcc, v188, v204, v188
	v_fma_f32 v208, -v205, v206, 1.0
	v_fmac_f32_e32 v206, v208, v206
	v_mul_f32_e32 v208, v207, v206
	v_fma_f32 v209, -v205, v208, v207
	v_fmac_f32_e32 v208, v209, v206
	v_fma_f32 v205, -v205, v208, v207
	v_div_fmas_f32 v205, v205, v206, v208
	v_div_fixup_f32 v188, v205, v204, v188
	ds_write_b32 v11, v188 offset:45056
	s_waitcnt vmcnt(12)
	v_mul_f32_e32 v204, 0xbfb8aa3b, v189
	v_exp_f32_e32 v204, v204
	s_nop 0
	v_add_f32_e32 v204, 1.0, v204
	v_div_scale_f32 v205, s[10:11], v204, v204, v189
	v_rcp_f32_e32 v206, v205
	v_div_scale_f32 v207, vcc, v189, v204, v189
	v_fma_f32 v208, -v205, v206, 1.0
	v_fmac_f32_e32 v206, v208, v206
	v_mul_f32_e32 v208, v207, v206
	v_fma_f32 v209, -v205, v208, v207
	v_fmac_f32_e32 v208, v209, v206
	v_fma_f32 v205, -v205, v208, v207
	v_div_fmas_f32 v205, v205, v206, v208
	v_div_fixup_f32 v189, v205, v204, v189
	ds_write_b32 v11, v189 offset:47104
	s_waitcnt vmcnt(11)
	v_mul_f32_e32 v204, 0xbfb8aa3b, v190
	v_exp_f32_e32 v204, v204
	s_nop 0
	v_add_f32_e32 v204, 1.0, v204
	v_div_scale_f32 v205, s[10:11], v204, v204, v190
	v_rcp_f32_e32 v206, v205
	v_div_scale_f32 v207, vcc, v190, v204, v190
	v_fma_f32 v208, -v205, v206, 1.0
	v_fmac_f32_e32 v206, v208, v206
	v_mul_f32_e32 v208, v207, v206
	v_fma_f32 v209, -v205, v208, v207
	v_fmac_f32_e32 v208, v209, v206
	v_fma_f32 v205, -v205, v208, v207
	v_div_fmas_f32 v205, v205, v206, v208
	v_div_fixup_f32 v190, v205, v204, v190
	ds_write_b32 v11, v190 offset:49152
	s_waitcnt vmcnt(10)
	v_mul_f32_e32 v204, 0xbfb8aa3b, v191
	v_exp_f32_e32 v204, v204
	s_nop 0
	v_add_f32_e32 v204, 1.0, v204
	v_div_scale_f32 v205, s[10:11], v204, v204, v191
	v_rcp_f32_e32 v206, v205
	v_div_scale_f32 v207, vcc, v191, v204, v191
	v_fma_f32 v208, -v205, v206, 1.0
	v_fmac_f32_e32 v206, v208, v206
	v_mul_f32_e32 v208, v207, v206
	v_fma_f32 v209, -v205, v208, v207
	v_fmac_f32_e32 v208, v209, v206
	v_fma_f32 v205, -v205, v208, v207
	v_div_fmas_f32 v205, v205, v206, v208
	v_div_fixup_f32 v191, v205, v204, v191
	ds_write_b32 v11, v191 offset:51200
	s_waitcnt vmcnt(9)
	v_mul_f32_e32 v204, 0xbfb8aa3b, v192
	v_exp_f32_e32 v204, v204
	s_nop 0
	v_add_f32_e32 v204, 1.0, v204
	v_div_scale_f32 v205, s[10:11], v204, v204, v192
	v_rcp_f32_e32 v206, v205
	v_div_scale_f32 v207, vcc, v192, v204, v192
	v_fma_f32 v208, -v205, v206, 1.0
	v_fmac_f32_e32 v206, v208, v206
	v_mul_f32_e32 v208, v207, v206
	v_fma_f32 v209, -v205, v208, v207
	v_fmac_f32_e32 v208, v209, v206
	v_fma_f32 v205, -v205, v208, v207
	v_div_fmas_f32 v205, v205, v206, v208
	v_div_fixup_f32 v192, v205, v204, v192
	ds_write_b32 v11, v192 offset:53248
	s_waitcnt vmcnt(8)
	v_mul_f32_e32 v204, 0xbfb8aa3b, v193
	v_exp_f32_e32 v204, v204
	s_nop 0
	v_add_f32_e32 v204, 1.0, v204
	v_div_scale_f32 v205, s[10:11], v204, v204, v193
	v_rcp_f32_e32 v206, v205
	v_div_scale_f32 v207, vcc, v193, v204, v193
	v_fma_f32 v208, -v205, v206, 1.0
	v_fmac_f32_e32 v206, v208, v206
	v_mul_f32_e32 v208, v207, v206
	v_fma_f32 v209, -v205, v208, v207
	v_fmac_f32_e32 v208, v209, v206
	v_fma_f32 v205, -v205, v208, v207
	v_div_fmas_f32 v205, v205, v206, v208
	v_div_fixup_f32 v193, v205, v204, v193
	ds_write_b32 v11, v193 offset:55296
	s_waitcnt vmcnt(7)
	v_mul_f32_e32 v204, 0xbfb8aa3b, v194
	v_exp_f32_e32 v204, v204
	s_nop 0
	v_add_f32_e32 v204, 1.0, v204
	v_div_scale_f32 v205, s[10:11], v204, v204, v194
	v_rcp_f32_e32 v206, v205
	v_div_scale_f32 v207, vcc, v194, v204, v194
	v_fma_f32 v208, -v205, v206, 1.0
	v_fmac_f32_e32 v206, v208, v206
	v_mul_f32_e32 v208, v207, v206
	v_fma_f32 v209, -v205, v208, v207
	v_fmac_f32_e32 v208, v209, v206
	v_fma_f32 v205, -v205, v208, v207
	v_div_fmas_f32 v205, v205, v206, v208
	v_div_fixup_f32 v194, v205, v204, v194
	ds_write_b32 v11, v194 offset:57344
	s_waitcnt vmcnt(6)
	v_mul_f32_e32 v204, 0xbfb8aa3b, v195
	v_exp_f32_e32 v204, v204
	s_nop 0
	v_add_f32_e32 v204, 1.0, v204
	v_div_scale_f32 v205, s[10:11], v204, v204, v195
	v_rcp_f32_e32 v206, v205
	v_div_scale_f32 v207, vcc, v195, v204, v195
	v_fma_f32 v208, -v205, v206, 1.0
	v_fmac_f32_e32 v206, v208, v206
	v_mul_f32_e32 v208, v207, v206
	v_fma_f32 v209, -v205, v208, v207
	v_fmac_f32_e32 v208, v209, v206
	v_fma_f32 v205, -v205, v208, v207
	v_div_fmas_f32 v205, v205, v206, v208
	v_div_fixup_f32 v195, v205, v204, v195
	ds_write_b32 v11, v195 offset:59392
	s_waitcnt vmcnt(5)
	v_mul_f32_e32 v204, 0xbfb8aa3b, v196
	v_exp_f32_e32 v204, v204
	s_nop 0
	v_add_f32_e32 v204, 1.0, v204
	v_div_scale_f32 v205, s[10:11], v204, v204, v196
	v_rcp_f32_e32 v206, v205
	v_div_scale_f32 v207, vcc, v196, v204, v196
	v_fma_f32 v208, -v205, v206, 1.0
	v_fmac_f32_e32 v206, v208, v206
	v_mul_f32_e32 v208, v207, v206
	v_fma_f32 v209, -v205, v208, v207
	v_fmac_f32_e32 v208, v209, v206
	v_fma_f32 v205, -v205, v208, v207
	v_div_fmas_f32 v205, v205, v206, v208
	v_div_fixup_f32 v196, v205, v204, v196
	ds_write_b32 v11, v196 offset:61440
	s_waitcnt vmcnt(4)
	v_mul_f32_e32 v204, 0xbfb8aa3b, v197
	v_exp_f32_e32 v204, v204
	s_nop 0
	v_add_f32_e32 v204, 1.0, v204
	v_div_scale_f32 v205, s[10:11], v204, v204, v197
	v_rcp_f32_e32 v206, v205
	v_div_scale_f32 v207, vcc, v197, v204, v197
	v_fma_f32 v208, -v205, v206, 1.0
	v_fmac_f32_e32 v206, v208, v206
	v_mul_f32_e32 v208, v207, v206
	v_fma_f32 v209, -v205, v208, v207
	v_fmac_f32_e32 v208, v209, v206
	v_fma_f32 v205, -v205, v208, v207
	v_div_fmas_f32 v205, v205, v206, v208
	v_div_fixup_f32 v197, v205, v204, v197
	ds_write_b32 v11, v197 offset:63488
	s_waitcnt vmcnt(3)
	v_mul_f32_e32 v204, 0xbfb8aa3b, v198
	v_exp_f32_e32 v204, v204
	s_nop 0
	v_add_f32_e32 v204, 1.0, v204
	v_div_scale_f32 v205, s[10:11], v204, v204, v198
	v_rcp_f32_e32 v206, v205
	v_div_scale_f32 v207, vcc, v198, v204, v198
	v_fma_f32 v208, -v205, v206, 1.0
	v_fmac_f32_e32 v206, v208, v206
	v_mul_f32_e32 v208, v207, v206
	v_fma_f32 v209, -v205, v208, v207
	v_fmac_f32_e32 v208, v209, v206
	v_fma_f32 v205, -v205, v208, v207
	v_div_fmas_f32 v205, v205, v206, v208
	v_div_fixup_f32 v198, v205, v204, v198
	ds_write_b32 v203, v198
	s_waitcnt vmcnt(2)
	v_mul_f32_e32 v204, 0xbfb8aa3b, v199
	v_exp_f32_e32 v204, v204
	s_nop 0
	v_add_f32_e32 v204, 1.0, v204
	v_div_scale_f32 v205, s[10:11], v204, v204, v199
	v_rcp_f32_e32 v206, v205
	v_div_scale_f32 v207, vcc, v199, v204, v199
	v_fma_f32 v208, -v205, v206, 1.0
	v_fmac_f32_e32 v206, v208, v206
	v_mul_f32_e32 v208, v207, v206
	v_fma_f32 v209, -v205, v208, v207
	v_fmac_f32_e32 v208, v209, v206
	v_fma_f32 v205, -v205, v208, v207
	v_div_fmas_f32 v205, v205, v206, v208
	v_div_fixup_f32 v199, v205, v204, v199
	ds_write_b32 v203, v199 offset:2048
	s_waitcnt vmcnt(1)
	v_mul_f32_e32 v204, 0xbfb8aa3b, v200
	v_exp_f32_e32 v204, v204
	s_nop 0
	v_add_f32_e32 v204, 1.0, v204
	v_div_scale_f32 v205, s[10:11], v204, v204, v200
	v_rcp_f32_e32 v206, v205
	v_div_scale_f32 v207, vcc, v200, v204, v200
	v_fma_f32 v208, -v205, v206, 1.0
	v_fmac_f32_e32 v206, v208, v206
	v_mul_f32_e32 v208, v207, v206
	v_fma_f32 v209, -v205, v208, v207
	v_fmac_f32_e32 v208, v209, v206
	v_fma_f32 v205, -v205, v208, v207
	v_div_fmas_f32 v205, v205, v206, v208
	v_div_fixup_f32 v200, v205, v204, v200
	ds_write_b32 v203, v200 offset:4096
	s_waitcnt vmcnt(0)
	v_mul_f32_e32 v204, 0xbfb8aa3b, v201
	v_exp_f32_e32 v204, v204
	s_nop 0
	v_add_f32_e32 v204, 1.0, v204
	v_div_scale_f32 v205, s[10:11], v204, v204, v201
	v_rcp_f32_e32 v206, v205
	v_div_scale_f32 v207, vcc, v201, v204, v201
	v_fma_f32 v208, -v205, v206, 1.0
	v_fmac_f32_e32 v206, v208, v206
	v_mul_f32_e32 v208, v207, v206
	v_fma_f32 v209, -v205, v208, v207
	v_fmac_f32_e32 v208, v209, v206
	v_fma_f32 v205, -v205, v208, v207
	v_div_fmas_f32 v205, v205, v206, v208
	v_div_fixup_f32 v201, v205, v204, v201
	ds_write_b32 v203, v201 offset:6144
